# PEER pass index: each XCD takes the token blocks of the GEMM panels owned by the XCD four away (concentrated, all remote); on top of v076
# speedup vs baseline: 1.0045x; 1.0027x over previous
.LBB0_13:
	v_readlane_b32 s0, v254, 16
	s_add_i32 s10, s0, -2
	s_and_b32 s0, s10, 0xff
	s_mul_i32 s0, s0, 37
	s_lshr_b32 s0, s0, 8
	s_sub_i32 s1, s10, s0
	s_bfe_u32 s1, s1, 0x70001
	s_add_i32 s1, s1, s0
	s_bfe_u32 s92, s1, 0x60002
	s_mul_i32 s0, s92, 7
	s_sub_i32 s0, s10, s0
	s_and_b32 s0, s0, 0xff
	v_writelane_b32 v254, s0, 18
	s_cmp_lt_i32 s0, 3
	s_mov_b64 s[0:1], -1
	s_cbranch_scc1 .LBB0_403
	v_readlane_b32 s0, v254, 18
	s_and_b32 s2, 0xffff, s0
	v_writelane_b32 v254, s91, 19
	s_cmp_lt_i32 s2, 4
	s_mov_b64 s[0:1], -1
	v_writelane_b32 v254, s92, 20
	s_cbranch_scc1 .LBB0_346
	s_cmp_lt_i32 s2, 5
	s_cbranch_scc1 .LBB0_207
	s_cmp_lg_u32 s2, 5
	s_cbranch_scc0 .LBB0_161
	v_readlane_b32 s0, v254, 3
	v_readlane_b32 s1, v254, 4
	v_readlane_b32 s2, v254, 5
	v_readlane_b32 s3, v254, 6
	s_mov_b64 s[14:15], s[0:1]
	s_mov_b64 s[0:1], s[2:3]
	s_mov_b32 s57, s61
	v_writelane_b32 v254, s0, 23
	v_mov_b32_e32 v133, v0
	s_nop 0
	v_writelane_b32 v254, s1, 24
	s_nop 0
	v_readlane_b32 s0, v254, 0
	s_mov_b32 s16, s0
	v_readlane_b32 s0, v254, 12
	v_readlane_b32 s1, v254, 13
	s_load_dword s0, s[0:1], 0x0
	s_waitcnt lgkmcnt(0)
	s_cmp_eq_u32 s0, 0x100
	s_cbranch_scc0 .Lpeer_noperm
	s_lshr_b32 s1, s16, 3
	s_add_i32 s16, s16, 4
	s_and_b32 s16, s16, 7
	s_lshl_b32 s16, s16, 5
	s_or_b32 s16, s16, s1
